# f9 + gate-GEMM epilogue: -log2e folded into row scale and bias (128 fewer VALU per lane per unit)
# speedup vs baseline: 1.0047x; 1.0047x over previous
; __device__ __forceinline__ float logsigmoidf_(float x) { return fminf(x, 0.f) - flog(1.0f + fexp(-fabsf(x))); }
;     __device__ __forceinline__ void operator()(const Acc& acc, const Unit& u, int wr, int wc, int fr, int fq) const {
;         const int row0 = u.pm * BM + wr * 64 + fr; const int colt = u.pn * BM + wc * 32 + 8 * fq;
;         if (u.pn >= 24) {
;             const int zc = ((u.pn < 28) ? 6144 + (u.pn - 24) * BM : (u.pn < 30) ? 7168 + (u.pn - 28) * BM : 2560 + (u.pn - 30) * BM) + wc * 32 + 8 * fq;
;             const bool isa = (u.pn >= 28 && u.pn < 30);
;             f32x4 bb[2][2];
; #pragma unroll
;             for (int bj = 0; bj < 2; ++bj)
; #pragma unroll
;                 for (int n = 0; n < 2; ++n) bb[bj][n] = isa ? *(const f32x4*)(b_alpha + (zc - 7168) + bj * HALF + 4 * n) : (f32x4){0.f, 0.f, 0.f, 0.f};
;             float rz[2][4];
; #pragma unroll
;             for (int ai = 0; ai < 2; ++ai)
; #pragma unroll
;                 for (int m = 0; m < 4; ++m) rz[ai][m] = rinvx[row0 + ai * HALF + m * 16] * (1.0f / 512.0f);
; #pragma unroll
;             for (int ai = 0; ai < 2; ++ai)
; #pragma unroll
;                 for (int m = 0; m < 4; ++m) { const int row = row0 + ai * HALF + m * 16; const float rs = rz[ai][m]; bf16* rowp = Z + (size_t)row * NZ + zc;
; #pragma unroll
;                     for (int bj = 0; bj < 2; ++bj) { f32x4 v0 = acc[ai][bj][m][0] * rs + bb[bj][0], v1 = acc[ai][bj][m][1] * rs + bb[bj][1];
;                         if (isa) {
; #pragma unroll
;                             for (int e = 0; e < 4; ++e) { v0[e] = logsigmoidf_(v0[e]) * 0.0625f; v1[e] = logsigmoidf_(v1[e]) * 0.0625f; } }
;                         u32x4 w; w.x = pk2(v0[0], v0[1]); w.y = pk2(v0[2], v0[3]); w.z = pk2(v1[0], v1[1]); w.w = pk2(v1[2], v1[3]);
;                         *(u32x4*)(rowp + bj * HALF) = w; } }
;             return;
;         }
;         f32x4 bv[2][2];
; #pragma unroll
;         for (int bj = 0; bj < 2; ++bj)
; #pragma unroll
;             for (int n = 0; n < 2; ++n) bv[bj][n] = *(const f32x4*)(b_gate + colt + bj * HALF + 4 * n);
;         float rsv[2][4];
; #pragma unroll
;         for (int ai = 0; ai < 2; ++ai)
; #pragma unroll
;             for (int m = 0; m < 4; ++m) rsv[ai][m] = rinvx[row0 + ai * HALF + m * 16] * (1.0f / 512.0f);
; #pragma unroll
;         for (int ai = 0; ai < 2; ++ai)
; #pragma unroll
.LBB0_570:
	s_nop 15
	s_nop 7
	v_lshl_add_u32 v24, s42, 8, v193
	s_lshl_b32 s1, s0, 8
	v_or_b32_e32 v22, 16, v24
	v_or_b32_e32 v20, 32, v24
	v_or_b32_e32 v18, 48, v24
	s_mov_b64 s[42:43], -1
	s_cmp_lt_i32 s0, 24
	v_ashrrev_i32_e32 v25, 31, v24
	v_add_u32_e32 v183, 0x80, v24
	v_add_u32_e32 v182, 0x90, v24
	v_add_u32_e32 v181, 0xa0, v24
	v_add_u32_e32 v180, 0xb0, v24
	v_ashrrev_i32_e32 v23, 31, v22
	v_ashrrev_i32_e32 v21, 31, v20
	v_ashrrev_i32_e32 v19, 31, v18
	s_cbranch_scc0 .LBB0_573
	v_or_b32_e32 v26, s1, v189
	v_ashrrev_i32_e32 v27, 31, v26
	v_lshl_add_u64 v[2:3], v[26:27], 2, s[44:45]
	v_lshl_add_u64 v[4:5], v[24:25], 2, s[20:21]
	v_lshl_add_u64 v[6:7], v[22:23], 2, s[20:21]
	v_lshl_add_u64 v[8:9], v[20:21], 2, s[20:21]
	v_lshl_add_u64 v[10:11], v[18:19], 2, s[20:21]
	global_load_dword v32, v[4:5], off
	global_load_dword v33, v[6:7], off
	global_load_dword v170, v[8:9], off
	global_load_dword v185, v[10:11], off
	global_load_dword v195, v[4:5], off offset:512
	global_load_dword v196, v[4:5], off offset:576
	global_load_dword v197, v[4:5], off offset:640
	global_load_dword v198, v[4:5], off offset:704
	global_load_dwordx4 v[14:17], v[2:3], off
	global_load_dwordx4 v[10:13], v[2:3], off offset:16
	global_load_dwordx4 v[6:9], v[2:3], off offset:512
	s_nop 0
	global_load_dwordx4 v[2:5], v[2:3], off offset:528
	v_mov_b64_e32 v[28:29], s[88:89]
	v_mad_i64_i32 v[30:31], s[42:43], v24, s62, v[28:29]
	v_lshl_add_u64 v[186:187], v[30:31], 0, v[26:27]
	s_waitcnt vmcnt(0)
	v_mul_f32_e32 v2, 0xbfb8aa3b, v2
	v_mul_f32_e32 v3, 0xbfb8aa3b, v3
	v_mul_f32_e32 v4, 0xbfb8aa3b, v4
	v_mul_f32_e32 v5, 0xbfb8aa3b, v5
	v_mul_f32_e32 v6, 0xbfb8aa3b, v6
	v_mul_f32_e32 v7, 0xbfb8aa3b, v7
	v_mul_f32_e32 v8, 0xbfb8aa3b, v8
	v_mul_f32_e32 v9, 0xbfb8aa3b, v9
	v_mul_f32_e32 v10, 0xbfb8aa3b, v10
	v_mul_f32_e32 v11, 0xbfb8aa3b, v11
	v_mul_f32_e32 v12, 0xbfb8aa3b, v12
	v_mul_f32_e32 v13, 0xbfb8aa3b, v13
	v_mul_f32_e32 v14, 0xbfb8aa3b, v14
	v_mul_f32_e32 v15, 0xbfb8aa3b, v15
	v_mul_f32_e32 v16, 0xbfb8aa3b, v16
	v_mul_f32_e32 v17, 0xbfb8aa3b, v17
	v_mul_f32_e32 v199, 0xbb38aa3b, v32
	v_mul_f32_e32 v200, 0xbb38aa3b, v33
	v_mul_f32_e32 v184, 0xbb38aa3b, v170
	v_mul_f32_e32 v170, 0xbb38aa3b, v185
	v_mul_f32_e32 v33, 0xbb38aa3b, v195
	v_mul_f32_e32 v32, 0xbb38aa3b, v196
	v_mul_f32_e32 v31, 0xbb38aa3b, v197
	v_mul_f32_e32 v30, 0xbb38aa3b, v198
	v_fma_f32 v185, v158, v199, v14
	v_fma_f32 v195, v154, v199, v10
	v_fma_f32 v196, v159, v199, v15
	v_fma_f32 v197, v155, v199, v11
	v_fma_f32 v198, v160, v199, v16
	v_fma_f32 v201, v156, v199, v12
	v_fma_f32 v202, v161, v199, v17
	v_fma_f32 v203, v157, v199, v13
	v_exp_f32_e32 v185, v185
	v_exp_f32_e32 v195, v195
	v_exp_f32_e32 v196, v196
	v_exp_f32_e32 v197, v197
	v_exp_f32_e32 v198, v198
	v_exp_f32_e32 v201, v201
	v_exp_f32_e32 v202, v202
	v_exp_f32_e32 v203, v203
	v_add_f32_e32 v185, 1.0, v185
	v_add_f32_e32 v195, 1.0, v195
	v_add_f32_e32 v196, 1.0, v196
	v_add_f32_e32 v197, 1.0, v197
	v_add_f32_e32 v198, 1.0, v198
	v_add_f32_e32 v201, 1.0, v201
	v_add_f32_e32 v202, 1.0, v202
	v_add_f32_e32 v203, 1.0, v203
	v_rcp_f32_e32 v185, v185
	v_rcp_f32_e32 v195, v195
	v_rcp_f32_e32 v196, v196
	v_rcp_f32_e32 v197, v197
	v_rcp_f32_e32 v198, v198
	v_rcp_f32_e32 v201, v201
	v_rcp_f32_e32 v202, v202
	v_rcp_f32_e32 v203, v203
	v_fma_f32 v185, v185, s72, 0.5
	v_fma_f32 v195, v195, s72, 0.5
	v_fma_f32 v196, v196, s72, 0.5
	v_fma_f32 v197, v197, s72, 0.5
	v_fma_f32 v198, v198, s72, 0.5
	v_fma_f32 v201, v201, s72, 0.5
	v_fma_f32 v202, v202, s72, 0.5
	v_fma_f32 v203, v203, s72, 0.5
	v_max_f32_e32 v185, 1.0, v185
	v_max_f32_e32 v195, 1.0, v195
	v_max_f32_e32 v196, 1.0, v196
	v_max_f32_e32 v197, 1.0, v197
	v_max_f32_e32 v198, 1.0, v198
	v_max_f32_e32 v201, 1.0, v201
	v_max_f32_e32 v202, 1.0, v202
	v_max_f32_e32 v203, 1.0, v203
	v_cvt_u32_f32_e32 v185, v185
	v_cvt_u32_f32_e32 v195, v195
	v_cvt_u32_f32_e32 v196, v196
	v_cvt_u32_f32_e32 v197, v197
	v_cvt_u32_f32_sdwa v198, v198 dst_sel:WORD_1 dst_unused:UNUSED_PAD src0_sel:DWORD
	v_cvt_u32_f32_sdwa v201, v201 dst_sel:WORD_1 dst_unused:UNUSED_PAD src0_sel:DWORD
	v_cvt_u32_f32_sdwa v202, v202 dst_sel:BYTE_3 dst_unused:UNUSED_PAD src0_sel:DWORD
	v_cvt_u32_f32_sdwa v203, v203 dst_sel:BYTE_3 dst_unused:UNUSED_PAD src0_sel:DWORD
	v_lshl_or_b32 v185, v196, 8, v185
	v_lshl_or_b32 v195, v197, 8, v195
	v_or3_b32 v196, v185, v198, v202
	v_or3_b32 v197, v195, v201, v203
	v_fma_f32 v204, v150, v199, v6
	v_fma_f32 v185, v146, v199, v2
	global_store_dwordx2 v[186:187], v[196:197], off
	v_fma_f32 v196, v151, v199, v7
	v_fma_f32 v197, v147, v199, v3
	v_fma_f32 v198, v152, v199, v8
	v_fma_f32 v201, v148, v199, v4
	v_fma_f32 v202, v153, v199, v9
	v_fma_f32 v199, v149, v199, v5
	v_exp_f32_e32 v204, v204
	v_exp_f32_e32 v185, v185
	v_exp_f32_e32 v196, v196
	v_exp_f32_e32 v197, v197
	v_exp_f32_e32 v198, v198
	v_exp_f32_e32 v201, v201
	v_exp_f32_e32 v202, v202
	v_exp_f32_e32 v199, v199
	v_add_f32_e32 v195, 1.0, v204
	v_add_f32_e32 v185, 1.0, v185
	v_add_f32_e32 v196, 1.0, v196
	v_add_f32_e32 v197, 1.0, v197
	v_rcp_f32_e32 v195, v195
	v_rcp_f32_e32 v185, v185
	v_rcp_f32_e32 v196, v196
	v_rcp_f32_e32 v197, v197
	v_add_f32_e32 v198, 1.0, v198
	v_add_f32_e32 v201, 1.0, v201
	v_add_f32_e32 v202, 1.0, v202
	v_add_f32_e32 v199, 1.0, v199
	v_rcp_f32_e32 v198, v198
	v_rcp_f32_e32 v201, v201
	v_rcp_f32_e32 v202, v202
	v_rcp_f32_e32 v199, v199
	v_fma_f32 v195, v195, s72, 0.5
	v_fma_f32 v185, v185, s72, 0.5
	v_fma_f32 v196, v196, s72, 0.5
	v_fma_f32 v197, v197, s72, 0.5
	v_max_f32_e32 v195, 1.0, v195
	v_max_f32_e32 v185, 1.0, v185
	v_max_f32_e32 v196, 1.0, v196
	v_max_f32_e32 v197, 1.0, v197
	v_fma_f32 v198, v198, s72, 0.5
	v_fma_f32 v201, v201, s72, 0.5
; __device__ __forceinline__ float sigmoidf_(float x) { return frcp(1.0f + fexp(-x)); }
;     __device__ __forceinline__ void operator()(const Acc& acc, const Unit& u, int wr, int wc, int fr, int fq) const {
;     ...
;             for (int m = 0; m < 4; ++m) { const int row = row0 + ai * HALF + m * 16; const float rs = rsv[ai][m]; unsigned char* rowp = GT + (size_t)row * NGT + colt;
; #pragma unroll
;                 for (int bj = 0; bj < 2; ++bj) { f32x4 v0 = acc[ai][bj][m][0] * rs + bv[bj][0], v1 = acc[ai][bj][m][1] * rs + bv[bj][1];
;                     unsigned q0[4], q1[4];
; #pragma unroll
;                     for (int e = 0; e < 4; ++e) { q0[e] = (unsigned)fmaxf(sigmoidf_(v0[e]) * 255.0f + 0.5f, 1.0f); q1[e] = (unsigned)fmaxf(sigmoidf_(v1[e]) * 255.0f + 0.5f, 1.0f); }
;                     u32x2 w; w.x = q0[0] | (q0[1] << 8) | (q0[2] << 16) | (q0[3] << 24); w.y = q1[0] | (q1[1] << 8) | (q1[2] << 16) | (q1[3] << 24);
;                     *(u32x2*)(rowp + bj * HALF) = w; } }
	v_fma_f32 v202, v202, s72, 0.5
	v_fma_f32 v199, v199, s72, 0.5
	v_cvt_u32_f32_e32 v195, v195
	v_cvt_u32_f32_e32 v185, v185
	v_cvt_u32_f32_e32 v196, v196
	v_cvt_u32_f32_e32 v197, v197
	v_max_f32_e32 v198, 1.0, v198
	v_max_f32_e32 v201, 1.0, v201
	v_max_f32_e32 v202, 1.0, v202
	v_max_f32_e32 v199, 1.0, v199
	v_cvt_u32_f32_sdwa v198, v198 dst_sel:WORD_1 dst_unused:UNUSED_PAD src0_sel:DWORD
	v_cvt_u32_f32_sdwa v201, v201 dst_sel:WORD_1 dst_unused:UNUSED_PAD src0_sel:DWORD
	v_cvt_u32_f32_sdwa v202, v202 dst_sel:BYTE_3 dst_unused:UNUSED_PAD src0_sel:DWORD
	v_cvt_u32_f32_sdwa v199, v199 dst_sel:BYTE_3 dst_unused:UNUSED_PAD src0_sel:DWORD
	v_lshl_or_b32 v195, v196, 8, v195
	v_lshl_or_b32 v185, v197, 8, v185
	v_or3_b32 v196, v195, v198, v202
	v_or3_b32 v197, v185, v201, v199
	global_store_dwordx2 v[186:187], v[196:197], off offset:128
	v_fma_f32 v185, v142, v200, v14
	v_fma_f32 v196, v143, v200, v15
	v_fma_f32 v195, v138, v200, v10
	v_fma_f32 v197, v139, v200, v11
	v_fma_f32 v198, v144, v200, v16
	v_fma_f32 v201, v145, v200, v17
	v_exp_f32_e32 v185, v185
	v_exp_f32_e32 v196, v196
	v_fma_f32 v199, v140, v200, v12
	v_fma_f32 v202, v141, v200, v13
	v_exp_f32_e32 v195, v195
	v_exp_f32_e32 v197, v197
	v_exp_f32_e32 v198, v198
	v_exp_f32_e32 v201, v201
	v_exp_f32_e32 v199, v199
	v_exp_f32_e32 v202, v202
	v_add_f32_e32 v185, 1.0, v185
	v_add_f32_e32 v196, 1.0, v196
	v_rcp_f32_e32 v185, v185
	v_add_f32_e32 v195, 1.0, v195
	v_rcp_f32_e32 v196, v196
	v_add_f32_e32 v197, 1.0, v197
	v_add_f32_e32 v198, 1.0, v198
	v_add_f32_e32 v201, 1.0, v201
	v_rcp_f32_e32 v195, v195
	v_rcp_f32_e32 v197, v197
	v_rcp_f32_e32 v198, v198
	v_add_f32_e32 v199, 1.0, v199
	v_rcp_f32_e32 v201, v201
	v_add_f32_e32 v202, 1.0, v202
	v_rcp_f32_e32 v199, v199
	v_rcp_f32_e32 v202, v202
	v_fma_f32 v185, v185, s72, 0.5
	v_fma_f32 v196, v196, s72, 0.5
	v_max_f32_e32 v185, 1.0, v185
	v_fma_f32 v195, v195, s72, 0.5
	v_max_f32_e32 v196, 1.0, v196
	v_fma_f32 v197, v197, s72, 0.5
	v_fma_f32 v198, v198, s72, 0.5
	v_fma_f32 v201, v201, s72, 0.5
	v_cvt_u32_f32_e32 v185, v185
	v_max_f32_e32 v195, 1.0, v195
	v_cvt_u32_f32_e32 v196, v196
	v_max_f32_e32 v197, 1.0, v197
	v_max_f32_e32 v198, 1.0, v198
	v_fma_f32 v199, v199, s72, 0.5
	v_max_f32_e32 v201, 1.0, v201
	v_fma_f32 v202, v202, s72, 0.5
	v_cvt_u32_f32_e32 v195, v195
	v_cvt_u32_f32_e32 v197, v197
	v_cvt_u32_f32_sdwa v198, v198 dst_sel:WORD_1 dst_unused:UNUSED_PAD src0_sel:DWORD
	v_max_f32_e32 v199, 1.0, v199
	v_cvt_u32_f32_sdwa v201, v201 dst_sel:BYTE_3 dst_unused:UNUSED_PAD src0_sel:DWORD
	v_max_f32_e32 v202, 1.0, v202
	v_cvt_u32_f32_sdwa v199, v199 dst_sel:WORD_1 dst_unused:UNUSED_PAD src0_sel:DWORD
	v_cvt_u32_f32_sdwa v202, v202 dst_sel:BYTE_3 dst_unused:UNUSED_PAD src0_sel:DWORD
	v_lshl_or_b32 v185, v196, 8, v185
	v_mad_i64_i32 v[186:187], s[42:43], v22, s62, v[28:29]
	v_or3_b32 v196, v185, v198, v201
	v_lshl_or_b32 v185, v197, 8, v195
	v_lshl_add_u64 v[186:187], v[186:187], 0, v[26:27]
	v_or3_b32 v197, v185, v199, v202
	v_fma_f32 v185, v134, v200, v6
	global_store_dwordx2 v[186:187], v[196:197], off
	v_fma_f32 v196, v135, v200, v7
	v_fma_f32 v195, v130, v200, v2
	v_fma_f32 v197, v131, v200, v3
	v_fma_f32 v198, v136, v200, v8
	v_fma_f32 v201, v137, v200, v9
	v_exp_f32_e32 v185, v185
	v_exp_f32_e32 v196, v196
	v_fma_f32 v199, v132, v200, v4
	v_fma_f32 v200, v133, v200, v5
	v_exp_f32_e32 v195, v195
	v_exp_f32_e32 v197, v197
	v_exp_f32_e32 v198, v198
	v_exp_f32_e32 v201, v201
	v_exp_f32_e32 v199, v199
	v_exp_f32_e32 v200, v200
	v_add_f32_e32 v185, 1.0, v185
	v_add_f32_e32 v196, 1.0, v196
	v_rcp_f32_e32 v185, v185
	v_add_f32_e32 v195, 1.0, v195
	v_rcp_f32_e32 v196, v196
	v_add_f32_e32 v197, 1.0, v197
	v_add_f32_e32 v198, 1.0, v198
	v_add_f32_e32 v201, 1.0, v201
	v_rcp_f32_e32 v195, v195
	v_rcp_f32_e32 v197, v197
	v_rcp_f32_e32 v198, v198
	v_add_f32_e32 v199, 1.0, v199
	v_rcp_f32_e32 v201, v201
	v_add_f32_e32 v200, 1.0, v200
	v_rcp_f32_e32 v199, v199
	v_rcp_f32_e32 v200, v200
	v_fma_f32 v185, v185, s72, 0.5
	v_fma_f32 v196, v196, s72, 0.5
	v_max_f32_e32 v185, 1.0, v185
	v_fma_f32 v195, v195, s72, 0.5
	v_max_f32_e32 v196, 1.0, v196
	v_fma_f32 v197, v197, s72, 0.5
	v_fma_f32 v198, v198, s72, 0.5
	v_fma_f32 v201, v201, s72, 0.5
	v_cvt_u32_f32_e32 v185, v185
	v_max_f32_e32 v195, 1.0, v195
	v_cvt_u32_f32_e32 v196, v196
	v_max_f32_e32 v197, 1.0, v197
	v_max_f32_e32 v198, 1.0, v198
	v_fma_f32 v199, v199, s72, 0.5
	v_max_f32_e32 v201, 1.0, v201
	v_fma_f32 v200, v200, s72, 0.5
	v_cvt_u32_f32_e32 v195, v195
	v_cvt_u32_f32_e32 v197, v197
	v_cvt_u32_f32_sdwa v198, v198 dst_sel:WORD_1 dst_unused:UNUSED_PAD src0_sel:DWORD
	v_max_f32_e32 v199, 1.0, v199
	v_cvt_u32_f32_sdwa v201, v201 dst_sel:BYTE_3 dst_unused:UNUSED_PAD src0_sel:DWORD
	v_max_f32_e32 v200, 1.0, v200
	v_cvt_u32_f32_sdwa v199, v199 dst_sel:WORD_1 dst_unused:UNUSED_PAD src0_sel:DWORD
	v_cvt_u32_f32_sdwa v200, v200 dst_sel:BYTE_3 dst_unused:UNUSED_PAD src0_sel:DWORD
	v_lshl_or_b32 v185, v196, 8, v185
	v_or3_b32 v196, v185, v198, v201
	v_lshl_or_b32 v185, v197, 8, v195
	v_or3_b32 v197, v185, v199, v200
	global_store_dwordx2 v[186:187], v[196:197], off offset:128
	v_fma_f32 v185, v126, v184, v14
	v_fma_f32 v196, v127, v184, v15
	v_fma_f32 v195, v122, v184, v10
	v_fma_f32 v197, v123, v184, v11
	v_fma_f32 v198, v128, v184, v16
	v_fma_f32 v200, v129, v184, v17
	v_exp_f32_e32 v185, v185
	v_exp_f32_e32 v196, v196
	v_fma_f32 v199, v124, v184, v12
	v_fma_f32 v201, v125, v184, v13
	v_exp_f32_e32 v195, v195
	v_exp_f32_e32 v197, v197
	v_exp_f32_e32 v198, v198
	v_exp_f32_e32 v200, v200
	v_exp_f32_e32 v199, v199
	v_exp_f32_e32 v201, v201
	v_add_f32_e32 v185, 1.0, v185
	v_add_f32_e32 v196, 1.0, v196
; __device__ __forceinline__ float sigmoidf_(float x) { return frcp(1.0f + fexp(-x)); }
;     __device__ __forceinline__ void operator()(const Acc& acc, const Unit& u, int wr, int wc, int fr, int fq) const {
;     ...
;             for (int m = 0; m < 4; ++m) { const int row = row0 + ai * HALF + m * 16; const float rs = rsv[ai][m]; unsigned char* rowp = GT + (size_t)row * NGT + colt;
; #pragma unroll
;                 for (int bj = 0; bj < 2; ++bj) { f32x4 v0 = acc[ai][bj][m][0] * rs + bv[bj][0], v1 = acc[ai][bj][m][1] * rs + bv[bj][1];
;                     unsigned q0[4], q1[4];
; #pragma unroll
;                     for (int e = 0; e < 4; ++e) { q0[e] = (unsigned)fmaxf(sigmoidf_(v0[e]) * 255.0f + 0.5f, 1.0f); q1[e] = (unsigned)fmaxf(sigmoidf_(v1[e]) * 255.0f + 0.5f, 1.0f); }
;                     u32x2 w; w.x = q0[0] | (q0[1] << 8) | (q0[2] << 16) | (q0[3] << 24); w.y = q1[0] | (q1[1] << 8) | (q1[2] << 16) | (q1[3] << 24);
;                     *(u32x2*)(rowp + bj * HALF) = w; } }
	v_rcp_f32_e32 v185, v185
	v_add_f32_e32 v195, 1.0, v195
	v_rcp_f32_e32 v196, v196
	v_add_f32_e32 v197, 1.0, v197
	v_add_f32_e32 v198, 1.0, v198
	v_add_f32_e32 v200, 1.0, v200
	v_rcp_f32_e32 v195, v195
	v_rcp_f32_e32 v197, v197
	v_rcp_f32_e32 v198, v198
	v_add_f32_e32 v199, 1.0, v199
	v_rcp_f32_e32 v200, v200
	v_add_f32_e32 v201, 1.0, v201
	v_rcp_f32_e32 v199, v199
	v_rcp_f32_e32 v201, v201
	v_fma_f32 v185, v185, s72, 0.5
	v_fma_f32 v196, v196, s72, 0.5
	v_max_f32_e32 v185, 1.0, v185
	v_fma_f32 v195, v195, s72, 0.5
	v_max_f32_e32 v196, 1.0, v196
	v_fma_f32 v197, v197, s72, 0.5
	v_fma_f32 v198, v198, s72, 0.5
	v_fma_f32 v200, v200, s72, 0.5
	v_cvt_u32_f32_e32 v185, v185
	v_max_f32_e32 v195, 1.0, v195
	v_cvt_u32_f32_e32 v196, v196
	v_max_f32_e32 v197, 1.0, v197
	v_max_f32_e32 v198, 1.0, v198
	v_fma_f32 v199, v199, s72, 0.5
	v_max_f32_e32 v200, 1.0, v200
	v_fma_f32 v201, v201, s72, 0.5
	v_cvt_u32_f32_e32 v195, v195
	v_cvt_u32_f32_e32 v197, v197
	v_cvt_u32_f32_sdwa v198, v198 dst_sel:WORD_1 dst_unused:UNUSED_PAD src0_sel:DWORD
	v_max_f32_e32 v199, 1.0, v199
	v_cvt_u32_f32_sdwa v200, v200 dst_sel:BYTE_3 dst_unused:UNUSED_PAD src0_sel:DWORD
	v_max_f32_e32 v201, 1.0, v201
	v_cvt_u32_f32_sdwa v199, v199 dst_sel:WORD_1 dst_unused:UNUSED_PAD src0_sel:DWORD
	v_cvt_u32_f32_sdwa v201, v201 dst_sel:BYTE_3 dst_unused:UNUSED_PAD src0_sel:DWORD
	v_lshl_or_b32 v185, v196, 8, v185
	v_mad_i64_i32 v[186:187], s[42:43], v20, s62, v[28:29]
	v_or3_b32 v196, v185, v198, v200
	v_lshl_or_b32 v185, v197, 8, v195
	v_lshl_add_u64 v[186:187], v[186:187], 0, v[26:27]
	v_or3_b32 v197, v185, v199, v201
	v_fma_f32 v185, v118, v184, v6
	v_fma_f32 v195, v114, v184, v2
	global_store_dwordx2 v[186:187], v[196:197], off
	v_fma_f32 v196, v119, v184, v7
	v_fma_f32 v197, v115, v184, v3
	v_fma_f32 v198, v120, v184, v8
	v_fma_f32 v199, v116, v184, v4
	v_fma_f32 v200, v121, v184, v9
	v_fma_f32 v184, v117, v184, v5
	v_exp_f32_e32 v185, v185
	v_exp_f32_e32 v195, v195
	v_exp_f32_e32 v196, v196
	v_exp_f32_e32 v197, v197
	v_exp_f32_e32 v198, v198
	v_exp_f32_e32 v199, v199
	v_exp_f32_e32 v200, v200
	v_exp_f32_e32 v184, v184
	v_add_f32_e32 v185, 1.0, v185
	v_add_f32_e32 v195, 1.0, v195
	v_add_f32_e32 v196, 1.0, v196
	v_add_f32_e32 v197, 1.0, v197
	v_rcp_f32_e32 v185, v185
	v_rcp_f32_e32 v195, v195
	v_rcp_f32_e32 v196, v196
	v_rcp_f32_e32 v197, v197
	v_add_f32_e32 v198, 1.0, v198
	v_add_f32_e32 v199, 1.0, v199
	v_add_f32_e32 v200, 1.0, v200
	v_add_f32_e32 v184, 1.0, v184
	v_rcp_f32_e32 v198, v198
	v_rcp_f32_e32 v199, v199
	v_rcp_f32_e32 v200, v200
	v_rcp_f32_e32 v184, v184
	v_fma_f32 v185, v185, s72, 0.5
	v_fma_f32 v195, v195, s72, 0.5
	v_fma_f32 v196, v196, s72, 0.5
	v_fma_f32 v197, v197, s72, 0.5
	v_max_f32_e32 v185, 1.0, v185
	v_max_f32_e32 v195, 1.0, v195
	v_max_f32_e32 v196, 1.0, v196
	v_max_f32_e32 v197, 1.0, v197
	v_fma_f32 v198, v198, s72, 0.5
	v_fma_f32 v199, v199, s72, 0.5
	v_fma_f32 v200, v200, s72, 0.5
	v_fma_f32 v184, v184, s72, 0.5
	v_cvt_u32_f32_e32 v185, v185
	v_cvt_u32_f32_e32 v195, v195
	v_cvt_u32_f32_e32 v196, v196
	v_cvt_u32_f32_e32 v197, v197
	v_max_f32_e32 v198, 1.0, v198
	v_max_f32_e32 v199, 1.0, v199
	v_max_f32_e32 v200, 1.0, v200
	v_max_f32_e32 v184, 1.0, v184
	v_cvt_u32_f32_sdwa v198, v198 dst_sel:WORD_1 dst_unused:UNUSED_PAD src0_sel:DWORD
	v_cvt_u32_f32_sdwa v199, v199 dst_sel:WORD_1 dst_unused:UNUSED_PAD src0_sel:DWORD
	v_cvt_u32_f32_sdwa v200, v200 dst_sel:BYTE_3 dst_unused:UNUSED_PAD src0_sel:DWORD
	v_cvt_u32_f32_sdwa v201, v184 dst_sel:BYTE_3 dst_unused:UNUSED_PAD src0_sel:DWORD
	v_lshl_or_b32 v184, v196, 8, v185
	v_lshl_or_b32 v185, v197, 8, v195
	v_or3_b32 v184, v184, v198, v200
	v_or3_b32 v185, v185, v199, v201
	global_store_dwordx2 v[186:187], v[184:185], off offset:128
	v_fma_f32 v187, v106, v170, v10
	v_fma_f32 v196, v107, v170, v11
	v_exp_f32_e32 v187, v187
	v_exp_f32_e32 v196, v196
	v_fma_f32 v186, v110, v170, v14
	v_fma_f32 v195, v111, v170, v15
	v_fma_f32 v197, v112, v170, v16
	v_fma_f32 v198, v108, v170, v12
	v_fma_f32 v199, v113, v170, v17
	v_fma_f32 v200, v109, v170, v13
	v_exp_f32_e32 v186, v186
	v_add_f32_e32 v187, 1.0, v187
	v_exp_f32_e32 v195, v195
	v_add_f32_e32 v196, 1.0, v196
	v_rcp_f32_e32 v187, v187
	v_rcp_f32_e32 v196, v196
	v_exp_f32_e32 v197, v197
	v_exp_f32_e32 v198, v198
	v_exp_f32_e32 v199, v199
	v_exp_f32_e32 v200, v200
	v_add_f32_e32 v186, 1.0, v186
	v_add_f32_e32 v195, 1.0, v195
	v_rcp_f32_e32 v186, v186
	v_fma_f32 v187, v187, s72, 0.5
	v_rcp_f32_e32 v195, v195
	v_fma_f32 v196, v196, s72, 0.5
	v_add_f32_e32 v197, 1.0, v197
	v_add_f32_e32 v198, 1.0, v198
	v_add_f32_e32 v199, 1.0, v199
	v_add_f32_e32 v200, 1.0, v200
	v_max_f32_e32 v187, 1.0, v187
	v_max_f32_e32 v196, 1.0, v196
	v_rcp_f32_e32 v197, v197
	v_rcp_f32_e32 v198, v198
	v_rcp_f32_e32 v199, v199
	v_rcp_f32_e32 v200, v200
	v_cvt_u32_f32_e32 v187, v187
	v_cvt_u32_f32_e32 v196, v196
	v_fma_f32 v186, v186, s72, 0.5
	v_fma_f32 v195, v195, s72, 0.5
	v_max_f32_e32 v186, 1.0, v186
	v_max_f32_e32 v195, 1.0, v195
	v_fma_f32 v197, v197, s72, 0.5
	v_fma_f32 v198, v198, s72, 0.5
	v_fma_f32 v199, v199, s72, 0.5
	v_fma_f32 v200, v200, s72, 0.5
	v_cvt_u32_f32_e32 v186, v186
	v_cvt_u32_f32_e32 v195, v195
	v_max_f32_e32 v197, 1.0, v197
	v_max_f32_e32 v198, 1.0, v198
	v_max_f32_e32 v199, 1.0, v199
	v_max_f32_e32 v200, 1.0, v200
	v_lshl_or_b32 v187, v196, 8, v187
	v_fma_f32 v196, v98, v170, v2
	v_cvt_u32_f32_sdwa v197, v197 dst_sel:WORD_1 dst_unused:UNUSED_PAD src0_sel:DWORD
	v_cvt_u32_f32_sdwa v198, v198 dst_sel:WORD_1 dst_unused:UNUSED_PAD src0_sel:DWORD
	v_cvt_u32_f32_sdwa v199, v199 dst_sel:BYTE_3 dst_unused:UNUSED_PAD src0_sel:DWORD
	v_cvt_u32_f32_sdwa v200, v200 dst_sel:BYTE_3 dst_unused:UNUSED_PAD src0_sel:DWORD
; __device__ __forceinline__ float sigmoidf_(float x) { return frcp(1.0f + fexp(-x)); }
;     __device__ __forceinline__ void operator()(const Acc& acc, const Unit& u, int wr, int wc, int fr, int fq) const {
;     ...
;             for (int m = 0; m < 4; ++m) { const int row = row0 + ai * HALF + m * 16; const float rs = rsv[ai][m]; unsigned char* rowp = GT + (size_t)row * NGT + colt;
; #pragma unroll
;                 for (int bj = 0; bj < 2; ++bj) { f32x4 v0 = acc[ai][bj][m][0] * rs + bv[bj][0], v1 = acc[ai][bj][m][1] * rs + bv[bj][1];
;                     unsigned q0[4], q1[4];
; #pragma unroll
;                     for (int e = 0; e < 4; ++e) { q0[e] = (unsigned)fmaxf(sigmoidf_(v0[e]) * 255.0f + 0.5f, 1.0f); q1[e] = (unsigned)fmaxf(sigmoidf_(v1[e]) * 255.0f + 0.5f, 1.0f); }
;                     u32x2 w; w.x = q0[0] | (q0[1] << 8) | (q0[2] << 16) | (q0[3] << 24); w.y = q1[0] | (q1[1] << 8) | (q1[2] << 16) | (q1[3] << 24);
;                     *(u32x2*)(rowp + bj * HALF) = w; } }
	v_exp_f32_e32 v196, v196
	v_mad_i64_i32 v[184:185], s[42:43], v18, s62, v[28:29]
	v_lshl_or_b32 v186, v195, 8, v186
	v_lshl_add_u64 v[184:185], v[184:185], 0, v[26:27]
	v_or3_b32 v186, v186, v197, v199
	v_or3_b32 v187, v187, v198, v200
	global_store_dwordx2 v[184:185], v[186:187], off
	v_add_f32_e32 v186, 1.0, v196
	v_rcp_f32_e32 v186, v186
	v_fma_f32 v196, v99, v170, v3
	v_fma_f32 v195, v102, v170, v6
	v_exp_f32_e32 v196, v196
	v_exp_f32_e32 v195, v195
	v_fma_f32 v186, v186, s72, 0.5
	v_max_f32_e32 v186, 1.0, v186
	v_cvt_u32_f32_e32 v197, v186
	v_add_f32_e32 v186, 1.0, v196
	v_add_f32_e32 v195, 1.0, v195
	v_rcp_f32_e32 v186, v186
	v_fma_f32 v198, v100, v170, v4
	v_rcp_f32_e32 v195, v195
	v_exp_f32_e32 v198, v198
	v_fma_f32 v186, v186, s72, 0.5
	v_fma_f32 v187, v195, s72, 0.5
	v_fma_f32 v195, v103, v170, v7
	v_max_f32_e32 v186, 1.0, v186
	v_fma_f32 v196, v104, v170, v8
	v_cvt_u32_f32_e32 v199, v186
	v_add_f32_e32 v186, 1.0, v198
	v_fma_f32 v198, v105, v170, v9
	v_exp_f32_e32 v195, v195
	v_fma_f32 v170, v101, v170, v5
	v_exp_f32_e32 v196, v196
	v_exp_f32_e32 v198, v198
	v_exp_f32_e32 v170, v170
	v_add_f32_e32 v195, 1.0, v195
	v_rcp_f32_e32 v186, v186
	v_rcp_f32_e32 v195, v195
	v_add_f32_e32 v196, 1.0, v196
	v_add_f32_e32 v198, 1.0, v198
	v_rcp_f32_e32 v196, v196
	v_rcp_f32_e32 v198, v198
	v_add_f32_e32 v170, 1.0, v170
	v_rcp_f32_e32 v170, v170
	v_fma_f32 v186, v186, s72, 0.5
	v_fma_f32 v195, v195, s72, 0.5
	v_max_f32_e32 v186, 1.0, v186
	v_max_f32_e32 v187, 1.0, v187
	v_max_f32_e32 v195, 1.0, v195
	v_fma_f32 v196, v196, s72, 0.5
	v_cvt_u32_f32_sdwa v200, v186 dst_sel:WORD_1 dst_unused:UNUSED_PAD src0_sel:DWORD
	v_fma_f32 v186, v198, s72, 0.5
	v_cvt_u32_f32_e32 v187, v187
	v_cvt_u32_f32_e32 v195, v195
	v_max_f32_e32 v196, 1.0, v196
	v_max_f32_e32 v186, 1.0, v186
	v_fma_f32 v170, v170, s72, 0.5
	v_cvt_u32_f32_sdwa v196, v196 dst_sel:WORD_1 dst_unused:UNUSED_PAD src0_sel:DWORD
	v_cvt_u32_f32_sdwa v186, v186 dst_sel:BYTE_3 dst_unused:UNUSED_PAD src0_sel:DWORD
	v_max_f32_e32 v170, 1.0, v170
	v_cvt_u32_f32_sdwa v170, v170 dst_sel:BYTE_3 dst_unused:UNUSED_PAD src0_sel:DWORD
	v_lshl_or_b32 v187, v195, 8, v187
	v_or3_b32 v186, v187, v196, v186
	v_lshl_or_b32 v187, v199, 8, v197
	v_or3_b32 v187, v187, v200, v170
	global_store_dwordx2 v[184:185], v[186:187], off offset:128
	v_fma_f32 v186, v90, v33, v10
	v_exp_f32_e32 v186, v186
	v_fma_f32 v195, v91, v33, v11
	v_exp_f32_e32 v195, v195
	v_add_f32_e32 v186, 1.0, v186
	v_rcp_f32_e32 v186, v186
	v_fma_f32 v197, v92, v33, v12
	v_exp_f32_e32 v197, v197
	v_fma_f32 v186, v186, s72, 0.5
	v_max_f32_e32 v186, 1.0, v186
	v_cvt_u32_f32_e32 v196, v186
	v_add_f32_e32 v186, 1.0, v195
	v_rcp_f32_e32 v186, v186
	v_fma_f32 v170, v94, v33, v14
	v_fma_f32 v187, v95, v33, v15
	v_fma_f32 v186, v186, s72, 0.5
	v_max_f32_e32 v186, 1.0, v186
	v_fma_f32 v195, v96, v33, v16
	v_cvt_u32_f32_e32 v198, v186
	v_add_f32_e32 v186, 1.0, v197
	v_fma_f32 v197, v97, v33, v17
	v_exp_f32_e32 v170, v170
	v_exp_f32_e32 v187, v187
	v_exp_f32_e32 v195, v195
	v_exp_f32_e32 v197, v197
	v_rcp_f32_e32 v186, v186
	v_fma_f32 v199, v93, v33, v13
	v_add_f32_e32 v170, 1.0, v170
	v_add_f32_e32 v187, 1.0, v187
	v_rcp_f32_e32 v170, v170
	v_rcp_f32_e32 v187, v187
	v_add_f32_e32 v195, 1.0, v195
	v_exp_f32_e32 v199, v199
	v_add_f32_e32 v197, 1.0, v197
	v_rcp_f32_e32 v195, v195
	v_rcp_f32_e32 v197, v197
	v_fma_f32 v186, v186, s72, 0.5
	v_max_f32_e32 v186, 1.0, v186
	v_fma_f32 v170, v170, s72, 0.5
	v_fma_f32 v187, v187, s72, 0.5
	v_cvt_u32_f32_sdwa v200, v186 dst_sel:WORD_1 dst_unused:UNUSED_PAD src0_sel:DWORD
	v_add_f32_e32 v186, 1.0, v199
	v_max_f32_e32 v170, 1.0, v170
	v_max_f32_e32 v187, 1.0, v187
	v_fma_f32 v195, v195, s72, 0.5
	v_rcp_f32_e32 v186, v186
	v_fma_f32 v197, v197, s72, 0.5
	v_cvt_u32_f32_e32 v170, v170
	v_cvt_u32_f32_e32 v187, v187
	v_max_f32_e32 v195, 1.0, v195
	v_max_f32_e32 v197, 1.0, v197
	v_cvt_u32_f32_sdwa v195, v195 dst_sel:WORD_1 dst_unused:UNUSED_PAD src0_sel:DWORD
	v_cvt_u32_f32_sdwa v197, v197 dst_sel:BYTE_3 dst_unused:UNUSED_PAD src0_sel:DWORD
	v_fma_f32 v186, v186, s72, 0.5
	v_max_f32_e32 v186, 1.0, v186
	v_lshl_or_b32 v170, v187, 8, v170
	v_cvt_u32_f32_sdwa v199, v186 dst_sel:BYTE_3 dst_unused:UNUSED_PAD src0_sel:DWORD
	v_or3_b32 v186, v170, v195, v197
	v_fma_f32 v195, v82, v33, v2
	v_exp_f32_e32 v195, v195
	v_mad_i64_i32 v[184:185], s[42:43], v183, s62, v[28:29]
	v_lshl_or_b32 v170, v198, 8, v196
	v_lshl_add_u64 v[184:185], v[184:185], 0, v[26:27]
	v_or3_b32 v187, v170, v200, v199
	global_store_dwordx2 v[184:185], v[186:187], off
	v_add_f32_e32 v186, 1.0, v195
	v_rcp_f32_e32 v186, v186
	v_fma_f32 v195, v83, v33, v3
	v_exp_f32_e32 v195, v195
	v_fma_f32 v186, v186, s72, 0.5
	v_max_f32_e32 v186, 1.0, v186
	v_cvt_u32_f32_e32 v196, v186
	v_add_f32_e32 v186, 1.0, v195
	v_rcp_f32_e32 v186, v186
	v_fma_f32 v197, v84, v33, v4
	v_exp_f32_e32 v197, v197
	v_fma_f32 v186, v186, s72, 0.5
	v_fma_f32 v170, v86, v33, v6
	v_fma_f32 v187, v87, v33, v7
	v_max_f32_e32 v186, 1.0, v186
	v_fma_f32 v195, v88, v33, v8
	v_cvt_u32_f32_e32 v198, v186
	v_add_f32_e32 v186, 1.0, v197
	v_fma_f32 v197, v89, v33, v9
	v_exp_f32_e32 v170, v170
	v_exp_f32_e32 v187, v187
	v_fma_f32 v33, v85, v33, v5
	v_exp_f32_e32 v195, v195
	v_exp_f32_e32 v197, v197
	v_exp_f32_e32 v33, v33
	v_add_f32_e32 v170, 1.0, v170
	v_add_f32_e32 v187, 1.0, v187
	v_rcp_f32_e32 v186, v186
	v_rcp_f32_e32 v170, v170
	v_rcp_f32_e32 v187, v187
	v_add_f32_e32 v195, 1.0, v195
	v_add_f32_e32 v197, 1.0, v197
	v_rcp_f32_e32 v195, v195
	v_rcp_f32_e32 v197, v197
	v_add_f32_e32 v33, 1.0, v33
	v_rcp_f32_e32 v33, v33
	v_fma_f32 v186, v186, s72, 0.5
	v_fma_f32 v170, v170, s72, 0.5
	v_fma_f32 v187, v187, s72, 0.5
; __device__ __forceinline__ float sigmoidf_(float x) { return frcp(1.0f + fexp(-x)); }
;     __device__ __forceinline__ void operator()(const Acc& acc, const Unit& u, int wr, int wc, int fr, int fq) const {
;     ...
;             for (int m = 0; m < 4; ++m) { const int row = row0 + ai * HALF + m * 16; const float rs = rsv[ai][m]; unsigned char* rowp = GT + (size_t)row * NGT + colt;
; #pragma unroll
;                 for (int bj = 0; bj < 2; ++bj) { f32x4 v0 = acc[ai][bj][m][0] * rs + bv[bj][0], v1 = acc[ai][bj][m][1] * rs + bv[bj][1];
;                     unsigned q0[4], q1[4];
; #pragma unroll
;                     for (int e = 0; e < 4; ++e) { q0[e] = (unsigned)fmaxf(sigmoidf_(v0[e]) * 255.0f + 0.5f, 1.0f); q1[e] = (unsigned)fmaxf(sigmoidf_(v1[e]) * 255.0f + 0.5f, 1.0f); }
;                     u32x2 w; w.x = q0[0] | (q0[1] << 8) | (q0[2] << 16) | (q0[3] << 24); w.y = q1[0] | (q1[1] << 8) | (q1[2] << 16) | (q1[3] << 24);
;                     *(u32x2*)(rowp + bj * HALF) = w; } }
	v_max_f32_e32 v186, 1.0, v186
	v_max_f32_e32 v170, 1.0, v170
	v_max_f32_e32 v187, 1.0, v187
	v_fma_f32 v195, v195, s72, 0.5
	v_cvt_u32_f32_sdwa v199, v186 dst_sel:WORD_1 dst_unused:UNUSED_PAD src0_sel:DWORD
	v_fma_f32 v186, v197, s72, 0.5
	v_cvt_u32_f32_e32 v170, v170
	v_cvt_u32_f32_e32 v187, v187
	v_max_f32_e32 v195, 1.0, v195
	v_max_f32_e32 v186, 1.0, v186
	v_fma_f32 v33, v33, s72, 0.5
	v_cvt_u32_f32_sdwa v195, v195 dst_sel:WORD_1 dst_unused:UNUSED_PAD src0_sel:DWORD
	v_cvt_u32_f32_sdwa v186, v186 dst_sel:BYTE_3 dst_unused:UNUSED_PAD src0_sel:DWORD
	v_max_f32_e32 v33, 1.0, v33
	v_cvt_u32_f32_sdwa v33, v33 dst_sel:BYTE_3 dst_unused:UNUSED_PAD src0_sel:DWORD
	v_lshl_or_b32 v170, v187, 8, v170
	v_or3_b32 v186, v170, v195, v186
	v_lshl_or_b32 v170, v198, 8, v196
	v_or3_b32 v187, v170, v199, v33
	global_store_dwordx2 v[184:185], v[186:187], off offset:128
	v_fma_f32 v33, v78, v32, v14
	v_fma_f32 v186, v79, v32, v15
	v_fma_f32 v170, v74, v32, v10
	v_fma_f32 v187, v75, v32, v11
	v_fma_f32 v195, v80, v32, v16
	v_fma_f32 v197, v81, v32, v17
	v_exp_f32_e32 v33, v33
	v_exp_f32_e32 v186, v186
	v_fma_f32 v196, v76, v32, v12
	v_fma_f32 v198, v77, v32, v13
	v_exp_f32_e32 v170, v170
	v_exp_f32_e32 v187, v187
	v_exp_f32_e32 v195, v195
	v_exp_f32_e32 v197, v197
	v_exp_f32_e32 v196, v196
	v_exp_f32_e32 v198, v198
	v_add_f32_e32 v33, 1.0, v33
	v_add_f32_e32 v186, 1.0, v186
	v_rcp_f32_e32 v33, v33
	v_add_f32_e32 v170, 1.0, v170
	v_rcp_f32_e32 v186, v186
	v_add_f32_e32 v187, 1.0, v187
	v_add_f32_e32 v195, 1.0, v195
	v_add_f32_e32 v197, 1.0, v197
	v_rcp_f32_e32 v170, v170
	v_rcp_f32_e32 v187, v187
	v_rcp_f32_e32 v195, v195
	v_add_f32_e32 v196, 1.0, v196
	v_rcp_f32_e32 v197, v197
	v_add_f32_e32 v198, 1.0, v198
	v_rcp_f32_e32 v196, v196
	v_rcp_f32_e32 v198, v198
	v_fma_f32 v33, v33, s72, 0.5
	v_fma_f32 v186, v186, s72, 0.5
	v_max_f32_e32 v33, 1.0, v33
	v_fma_f32 v170, v170, s72, 0.5
	v_max_f32_e32 v186, 1.0, v186
	v_fma_f32 v187, v187, s72, 0.5
	v_fma_f32 v195, v195, s72, 0.5
	v_fma_f32 v197, v197, s72, 0.5
	v_cvt_u32_f32_e32 v33, v33
	v_max_f32_e32 v170, 1.0, v170
	v_cvt_u32_f32_e32 v186, v186
	v_max_f32_e32 v187, 1.0, v187
	v_max_f32_e32 v195, 1.0, v195
	v_fma_f32 v196, v196, s72, 0.5
	v_max_f32_e32 v197, 1.0, v197
	v_fma_f32 v198, v198, s72, 0.5
	v_cvt_u32_f32_e32 v170, v170
	v_cvt_u32_f32_e32 v187, v187
	v_cvt_u32_f32_sdwa v195, v195 dst_sel:WORD_1 dst_unused:UNUSED_PAD src0_sel:DWORD
	v_max_f32_e32 v196, 1.0, v196
	v_cvt_u32_f32_sdwa v197, v197 dst_sel:BYTE_3 dst_unused:UNUSED_PAD src0_sel:DWORD
	v_max_f32_e32 v198, 1.0, v198
	v_cvt_u32_f32_sdwa v196, v196 dst_sel:WORD_1 dst_unused:UNUSED_PAD src0_sel:DWORD
	v_cvt_u32_f32_sdwa v198, v198 dst_sel:BYTE_3 dst_unused:UNUSED_PAD src0_sel:DWORD
	v_lshl_or_b32 v33, v186, 8, v33
	v_mad_i64_i32 v[184:185], s[42:43], v182, s62, v[28:29]
	v_or3_b32 v186, v33, v195, v197
	v_lshl_or_b32 v33, v187, 8, v170
	v_lshl_add_u64 v[184:185], v[184:185], 0, v[26:27]
	v_or3_b32 v187, v33, v196, v198
	v_fma_f32 v33, v70, v32, v6
	v_fma_f32 v170, v66, v32, v2
	global_store_dwordx2 v[184:185], v[186:187], off
	v_fma_f32 v186, v71, v32, v7
	v_fma_f32 v187, v67, v32, v3
	v_fma_f32 v195, v72, v32, v8
	v_fma_f32 v196, v68, v32, v4
	v_fma_f32 v197, v73, v32, v9
	v_fma_f32 v32, v69, v32, v5
	v_exp_f32_e32 v33, v33
	v_exp_f32_e32 v170, v170
	v_exp_f32_e32 v186, v186
	v_exp_f32_e32 v187, v187
	v_exp_f32_e32 v195, v195
	v_exp_f32_e32 v196, v196
	v_exp_f32_e32 v197, v197
	v_exp_f32_e32 v32, v32
	v_add_f32_e32 v33, 1.0, v33
	v_add_f32_e32 v170, 1.0, v170
	v_add_f32_e32 v186, 1.0, v186
	v_add_f32_e32 v187, 1.0, v187
	v_rcp_f32_e32 v33, v33
	v_rcp_f32_e32 v170, v170
	v_rcp_f32_e32 v186, v186
	v_rcp_f32_e32 v187, v187
	v_add_f32_e32 v195, 1.0, v195
	v_add_f32_e32 v196, 1.0, v196
	v_add_f32_e32 v197, 1.0, v197
	v_add_f32_e32 v32, 1.0, v32
	v_rcp_f32_e32 v195, v195
	v_rcp_f32_e32 v196, v196
	v_rcp_f32_e32 v197, v197
	v_rcp_f32_e32 v32, v32
	v_fma_f32 v33, v33, s72, 0.5
	v_fma_f32 v170, v170, s72, 0.5
	v_fma_f32 v186, v186, s72, 0.5
	v_fma_f32 v187, v187, s72, 0.5
	v_max_f32_e32 v33, 1.0, v33
	v_max_f32_e32 v170, 1.0, v170
	v_max_f32_e32 v186, 1.0, v186
	v_max_f32_e32 v187, 1.0, v187
	v_fma_f32 v195, v195, s72, 0.5
	v_fma_f32 v196, v196, s72, 0.5
	v_fma_f32 v197, v197, s72, 0.5
	v_fma_f32 v32, v32, s72, 0.5
	v_cvt_u32_f32_e32 v33, v33
	v_cvt_u32_f32_e32 v170, v170
	v_cvt_u32_f32_e32 v186, v186
	v_cvt_u32_f32_e32 v187, v187
	v_max_f32_e32 v195, 1.0, v195
	v_max_f32_e32 v196, 1.0, v196
	v_max_f32_e32 v197, 1.0, v197
	v_max_f32_e32 v32, 1.0, v32
	v_cvt_u32_f32_sdwa v195, v195 dst_sel:WORD_1 dst_unused:UNUSED_PAD src0_sel:DWORD
	v_cvt_u32_f32_sdwa v196, v196 dst_sel:WORD_1 dst_unused:UNUSED_PAD src0_sel:DWORD
	v_cvt_u32_f32_sdwa v197, v197 dst_sel:BYTE_3 dst_unused:UNUSED_PAD src0_sel:DWORD
	v_cvt_u32_f32_sdwa v198, v32 dst_sel:BYTE_3 dst_unused:UNUSED_PAD src0_sel:DWORD
	v_lshl_or_b32 v32, v186, 8, v33
	v_lshl_or_b32 v33, v187, 8, v170
	v_or3_b32 v32, v32, v195, v197
	v_or3_b32 v33, v33, v196, v198
	global_store_dwordx2 v[184:185], v[32:33], off offset:128
	v_fma_f32 v184, v58, v31, v10
	v_exp_f32_e32 v184, v184
	v_fma_f32 v186, v59, v31, v11
	v_exp_f32_e32 v186, v186
	v_add_f32_e32 v184, 1.0, v184
	v_rcp_f32_e32 v184, v184
	v_fma_f32 v10, v42, v30, v10
	v_fma_f32 v185, v63, v31, v15
	v_fma_f32 v184, v184, s72, 0.5
	v_exp_f32_e32 v10, v10
	v_fma_f32 v15, v47, v30, v15
	v_max_f32_e32 v184, 1.0, v184
	v_cvt_u32_f32_e32 v187, v184
	v_add_f32_e32 v184, 1.0, v186
	v_exp_f32_e32 v15, v15
	v_rcp_f32_e32 v184, v184
	v_fma_f32 v195, v60, v31, v12
	v_add_f32_e32 v10, 1.0, v10
	v_exp_f32_e32 v195, v195
	v_rcp_f32_e32 v10, v10
	v_fma_f32 v11, v43, v30, v11
; __device__ __forceinline__ float sigmoidf_(float x) { return frcp(1.0f + fexp(-x)); }
;     __device__ __forceinline__ void operator()(const Acc& acc, const Unit& u, int wr, int wc, int fr, int fq) const {
;     ...
;             for (int m = 0; m < 4; ++m) { const int row = row0 + ai * HALF + m * 16; const float rs = rsv[ai][m]; unsigned char* rowp = GT + (size_t)row * NGT + colt;
; #pragma unroll
;                 for (int bj = 0; bj < 2; ++bj) { f32x4 v0 = acc[ai][bj][m][0] * rs + bv[bj][0], v1 = acc[ai][bj][m][1] * rs + bv[bj][1];
;                     unsigned q0[4], q1[4];
; #pragma unroll
;                     for (int e = 0; e < 4; ++e) { q0[e] = (unsigned)fmaxf(sigmoidf_(v0[e]) * 255.0f + 0.5f, 1.0f); q1[e] = (unsigned)fmaxf(sigmoidf_(v1[e]) * 255.0f + 0.5f, 1.0f); }
;                     u32x2 w; w.x = q0[0] | (q0[1] << 8) | (q0[2] << 16) | (q0[3] << 24); w.y = q1[0] | (q1[1] << 8) | (q1[2] << 16) | (q1[3] << 24);
;                     *(u32x2*)(rowp + bj * HALF) = w; } }
	v_add_f32_e32 v15, 1.0, v15
	v_fma_f32 v184, v184, s72, 0.5
	v_exp_f32_e32 v11, v11
	v_rcp_f32_e32 v15, v15
	v_fma_f32 v170, v62, v31, v14
	v_max_f32_e32 v184, 1.0, v184
	v_fma_f32 v186, v64, v31, v16
	v_cvt_u32_f32_e32 v196, v184
	v_add_f32_e32 v184, 1.0, v195
	v_fma_f32 v195, v65, v31, v17
	v_fma_f32 v10, v10, s72, 0.5
	v_mad_i64_i32 v[32:33], s[42:43], v181, s62, v[28:29]
	v_exp_f32_e32 v170, v170
	v_exp_f32_e32 v185, v185
	v_rcp_f32_e32 v184, v184
	v_fma_f32 v197, v61, v31, v13
	v_mad_i64_i32 v[28:29], s[42:43], v180, s62, v[28:29]
	v_max_f32_e32 v10, 1.0, v10
	v_lshl_add_u64 v[32:33], v[32:33], 0, v[26:27]
	v_exp_f32_e32 v186, v186
	v_exp_f32_e32 v195, v195
	v_lshl_add_u64 v[26:27], v[28:29], 0, v[26:27]
	v_cvt_u32_f32_e32 v28, v10
	v_add_f32_e32 v10, 1.0, v11
	v_fma_f32 v11, v15, s72, 0.5
	v_fma_f32 v15, v48, v30, v16
	v_exp_f32_e32 v197, v197
	v_exp_f32_e32 v15, v15
	v_add_f32_e32 v170, 1.0, v170
	v_add_f32_e32 v185, 1.0, v185
	v_fma_f32 v184, v184, s72, 0.5
	v_rcp_f32_e32 v10, v10
	v_fma_f32 v12, v44, v30, v12
	v_rcp_f32_e32 v170, v170
	v_rcp_f32_e32 v185, v185
	v_add_f32_e32 v186, 1.0, v186
	v_max_f32_e32 v184, 1.0, v184
	v_add_f32_e32 v195, 1.0, v195
	v_rcp_f32_e32 v186, v186
	v_rcp_f32_e32 v195, v195
	v_cvt_u32_f32_sdwa v198, v184 dst_sel:WORD_1 dst_unused:UNUSED_PAD src0_sel:DWORD
	v_add_f32_e32 v184, 1.0, v197
	v_exp_f32_e32 v12, v12
	v_rcp_f32_e32 v184, v184
	v_add_f32_e32 v15, 1.0, v15
	v_fma_f32 v10, v10, s72, 0.5
	v_rcp_f32_e32 v15, v15
	v_fma_f32 v170, v170, s72, 0.5
	v_fma_f32 v185, v185, s72, 0.5
	v_max_f32_e32 v10, 1.0, v10
	v_max_f32_e32 v170, 1.0, v170
	v_max_f32_e32 v185, 1.0, v185
	v_fma_f32 v186, v186, s72, 0.5
	v_fma_f32 v195, v195, s72, 0.5
	v_fma_f32 v14, v46, v30, v14
	v_cvt_u32_f32_e32 v16, v10
	v_add_f32_e32 v10, 1.0, v12
	v_cvt_u32_f32_e32 v170, v170
	v_cvt_u32_f32_e32 v185, v185
	v_max_f32_e32 v186, 1.0, v186
	v_max_f32_e32 v195, 1.0, v195
	v_fma_f32 v184, v184, s72, 0.5
	v_rcp_f32_e32 v10, v10
	v_fmac_f32_e32 v17, v49, v30
	v_fmac_f32_e32 v13, v45, v30
	v_cvt_u32_f32_sdwa v186, v186 dst_sel:WORD_1 dst_unused:UNUSED_PAD src0_sel:DWORD
	v_cvt_u32_f32_sdwa v195, v195 dst_sel:BYTE_3 dst_unused:UNUSED_PAD src0_sel:DWORD
	v_max_f32_e32 v184, 1.0, v184
	v_exp_f32_e32 v14, v14
	v_fma_f32 v12, v15, s72, 0.5
	v_mov_b32_e32 v15, v17
	v_cvt_u32_f32_sdwa v197, v184 dst_sel:BYTE_3 dst_unused:UNUSED_PAD src0_sel:DWORD
	v_exp_f32_e32 v15, v15
	v_exp_f32_e32 v13, v13
	v_lshl_or_b32 v170, v185, 8, v170
	v_fma_f32 v10, v10, s72, 0.5
	v_or3_b32 v184, v170, v186, v195
	v_lshl_or_b32 v170, v196, 8, v187
	v_fma_f32 v186, v50, v31, v2
	v_add_f32_e32 v14, 1.0, v14
	v_max_f32_e32 v10, 1.0, v10
	v_fma_f32 v2, v34, v30, v2
	v_or3_b32 v185, v170, v198, v197
	v_rcp_f32_e32 v14, v14
	v_add_f32_e32 v15, 1.0, v15
	v_cvt_u32_f32_sdwa v17, v10 dst_sel:WORD_1 dst_unused:UNUSED_PAD src0_sel:DWORD
	v_add_f32_e32 v10, 1.0, v13
	global_store_dwordx2 v[32:33], v[184:185], off
	v_fma_f32 v185, v55, v31, v7
	v_rcp_f32_e32 v15, v15
	v_rcp_f32_e32 v10, v10
	v_exp_f32_e32 v2, v2
	v_fma_f32 v7, v39, v30, v7
	v_exp_f32_e32 v186, v186
	v_exp_f32_e32 v7, v7
	v_fma_f32 v14, v14, s72, 0.5
	v_max_f32_e32 v14, 1.0, v14
	v_max_f32_e32 v11, 1.0, v11
	v_fma_f32 v13, v15, s72, 0.5
	v_fma_f32 v10, v10, s72, 0.5
	v_add_f32_e32 v2, 1.0, v2
	v_add_f32_e32 v184, 1.0, v186
	v_fma_f32 v186, v51, v31, v3
	v_cvt_u32_f32_e32 v14, v14
	v_cvt_u32_f32_e32 v11, v11
	v_max_f32_e32 v12, 1.0, v12
	v_max_f32_e32 v13, 1.0, v13
	v_max_f32_e32 v10, 1.0, v10
	v_rcp_f32_e32 v2, v2
	v_fma_f32 v3, v35, v30, v3
	v_cvt_u32_f32_sdwa v12, v12 dst_sel:WORD_1 dst_unused:UNUSED_PAD src0_sel:DWORD
	v_cvt_u32_f32_sdwa v13, v13 dst_sel:BYTE_3 dst_unused:UNUSED_PAD src0_sel:DWORD
	v_cvt_u32_f32_sdwa v15, v10 dst_sel:BYTE_3 dst_unused:UNUSED_PAD src0_sel:DWORD
; __device__ __forceinline__ float sigmoidf_(float x) { return frcp(1.0f + fexp(-x)); }
;     __device__ __forceinline__ void operator()(const Acc& acc, const Unit& u, int wr, int wc, int fr, int fq) const {
;     ...
;             for (int m = 0; m < 4; ++m) { const int row = row0 + ai * HALF + m * 16; const float rs = rsv[ai][m]; unsigned char* rowp = GT + (size_t)row * NGT + colt;
; #pragma unroll
;                 for (int bj = 0; bj < 2; ++bj) { f32x4 v0 = acc[ai][bj][m][0] * rs + bv[bj][0], v1 = acc[ai][bj][m][1] * rs + bv[bj][1];
;                     unsigned q0[4], q1[4];
; #pragma unroll
;                     for (int e = 0; e < 4; ++e) { q0[e] = (unsigned)fmaxf(sigmoidf_(v0[e]) * 255.0f + 0.5f, 1.0f); q1[e] = (unsigned)fmaxf(sigmoidf_(v1[e]) * 255.0f + 0.5f, 1.0f); }
;                     u32x2 w; w.x = q0[0] | (q0[1] << 8) | (q0[2] << 16) | (q0[3] << 24); w.y = q1[0] | (q1[1] << 8) | (q1[2] << 16) | (q1[3] << 24);
;                     *(u32x2*)(rowp + bj * HALF) = w; } }
	v_add_f32_e32 v7, 1.0, v7
	v_rcp_f32_e32 v184, v184
	v_exp_f32_e32 v3, v3
	v_rcp_f32_e32 v7, v7
	v_exp_f32_e32 v186, v186
	v_lshl_or_b32 v10, v11, 8, v14
	v_lshl_or_b32 v11, v16, 8, v28
	v_fma_f32 v2, v2, s72, 0.5
	v_or3_b32 v10, v10, v12, v13
	v_or3_b32 v11, v11, v17, v15
	v_max_f32_e32 v2, 1.0, v2
	v_fma_f32 v184, v184, s72, 0.5
	global_store_dwordx2 v[26:27], v[10:11], off
	v_cvt_u32_f32_e32 v10, v2
	v_add_f32_e32 v2, 1.0, v3
	v_fma_f32 v3, v7, s72, 0.5
	v_fma_f32 v7, v40, v30, v8
	v_max_f32_e32 v184, 1.0, v184
	v_cvt_u32_f32_e32 v187, v184
	v_add_f32_e32 v184, 1.0, v186
	v_exp_f32_e32 v7, v7
	v_rcp_f32_e32 v184, v184
	v_fma_f32 v195, v52, v31, v4
	v_rcp_f32_e32 v2, v2
	v_fma_f32 v4, v36, v30, v4
	v_exp_f32_e32 v195, v195
	v_exp_f32_e32 v4, v4
	v_add_f32_e32 v7, 1.0, v7
	v_fma_f32 v184, v184, s72, 0.5
	v_fma_f32 v2, v2, s72, 0.5
	v_rcp_f32_e32 v7, v7
	v_fma_f32 v170, v54, v31, v6
	v_max_f32_e32 v184, 1.0, v184
	v_max_f32_e32 v2, 1.0, v2
	v_fma_f32 v186, v56, v31, v8
	v_cvt_u32_f32_e32 v196, v184
	v_add_f32_e32 v184, 1.0, v195
	v_fma_f32 v195, v57, v31, v9
	v_fma_f32 v6, v38, v30, v6
	v_cvt_u32_f32_e32 v8, v2
	v_add_f32_e32 v2, 1.0, v4
	v_exp_f32_e32 v170, v170
	v_exp_f32_e32 v185, v185
	v_fma_f32 v31, v53, v31, v5
	v_rcp_f32_e32 v2, v2
	v_fmac_f32_e32 v9, v41, v30
	v_fmac_f32_e32 v5, v37, v30
	v_exp_f32_e32 v186, v186
	v_exp_f32_e32 v195, v195
	v_exp_f32_e32 v6, v6
	v_fma_f32 v4, v7, s72, 0.5
	v_mov_b32_e32 v7, v9
	v_exp_f32_e32 v31, v31
	v_exp_f32_e32 v7, v7
	v_exp_f32_e32 v5, v5
	v_add_f32_e32 v170, 1.0, v170
	v_add_f32_e32 v185, 1.0, v185
	v_rcp_f32_e32 v184, v184
	v_fma_f32 v2, v2, s72, 0.5
	v_rcp_f32_e32 v170, v170
	v_rcp_f32_e32 v185, v185
	v_add_f32_e32 v186, 1.0, v186
	v_add_f32_e32 v195, 1.0, v195
	v_add_f32_e32 v6, 1.0, v6
	v_max_f32_e32 v2, 1.0, v2
	v_rcp_f32_e32 v186, v186
	v_rcp_f32_e32 v195, v195
	v_add_f32_e32 v31, 1.0, v31
	v_rcp_f32_e32 v6, v6
	v_add_f32_e32 v7, 1.0, v7
	v_cvt_u32_f32_sdwa v9, v2 dst_sel:WORD_1 dst_unused:UNUSED_PAD src0_sel:DWORD
	v_add_f32_e32 v2, 1.0, v5
	v_rcp_f32_e32 v31, v31
	v_rcp_f32_e32 v7, v7
	v_rcp_f32_e32 v2, v2
	v_fma_f32 v184, v184, s72, 0.5
	v_fma_f32 v170, v170, s72, 0.5
	v_fma_f32 v185, v185, s72, 0.5
	v_max_f32_e32 v184, 1.0, v184
	v_max_f32_e32 v170, 1.0, v170
	v_max_f32_e32 v185, 1.0, v185
	v_fma_f32 v186, v186, s72, 0.5
	v_cvt_u32_f32_sdwa v197, v184 dst_sel:WORD_1 dst_unused:UNUSED_PAD src0_sel:DWORD
	v_fma_f32 v184, v195, s72, 0.5
	v_fma_f32 v6, v6, s72, 0.5
	v_cvt_u32_f32_e32 v170, v170
	v_cvt_u32_f32_e32 v185, v185
	v_max_f32_e32 v186, 1.0, v186
	v_max_f32_e32 v184, 1.0, v184
	v_fma_f32 v31, v31, s72, 0.5
	v_max_f32_e32 v6, 1.0, v6
	v_max_f32_e32 v3, 1.0, v3
	v_fma_f32 v5, v7, s72, 0.5
	v_fma_f32 v2, v2, s72, 0.5
	v_cvt_u32_f32_sdwa v186, v186 dst_sel:WORD_1 dst_unused:UNUSED_PAD src0_sel:DWORD
	v_cvt_u32_f32_sdwa v184, v184 dst_sel:BYTE_3 dst_unused:UNUSED_PAD src0_sel:DWORD
	v_max_f32_e32 v31, 1.0, v31
	v_cvt_u32_f32_e32 v6, v6
	v_cvt_u32_f32_e32 v3, v3
	v_max_f32_e32 v4, 1.0, v4
	v_max_f32_e32 v5, 1.0, v5
	v_max_f32_e32 v2, 1.0, v2
	v_cvt_u32_f32_sdwa v31, v31 dst_sel:BYTE_3 dst_unused:UNUSED_PAD src0_sel:DWORD
	v_cvt_u32_f32_sdwa v4, v4 dst_sel:WORD_1 dst_unused:UNUSED_PAD src0_sel:DWORD
	v_cvt_u32_f32_sdwa v5, v5 dst_sel:BYTE_3 dst_unused:UNUSED_PAD src0_sel:DWORD
	v_cvt_u32_f32_sdwa v7, v2 dst_sel:BYTE_3 dst_unused:UNUSED_PAD src0_sel:DWORD
	v_lshl_or_b32 v170, v185, 8, v170
	v_or3_b32 v184, v170, v186, v184
	v_lshl_or_b32 v170, v196, 8, v187
	v_lshl_or_b32 v2, v3, 8, v6
	v_lshl_or_b32 v3, v8, 8, v10
	v_or3_b32 v185, v170, v197, v31
	v_or3_b32 v2, v2, v4, v5
	v_or3_b32 v3, v3, v9, v7
	global_store_dwordx2 v[32:33], v[184:185], off offset:128
	global_store_dwordx2 v[26:27], v[2:3], off offset:128
	s_cbranch_execz .LBB0_574
